# rfactor rows moved to otherwise idle workgroups
# baseline (speedup 1.0000x reference)
; __device__ __forceinline__ void rfactor_phase(const float* SS, float* R) {
;     PHASE_IDS;
;     for (int row = blockIdx.x * 512 + tid; row < MLAT; row += gridDim.x * 512) {
;         const f32x4* p = (const f32x4*)(SS + (size_t)row * 16); const f32x4 a = p[0], b = p[1], c = p[2], d = p[3];
;         const float t = ((a[0] + a[1]) + (a[2] + a[3])) + ((b[0] + b[1]) + (b[2] + b[3])) + ((c[0] + c[1]) + (c[2] + c[3])) + ((d[0] + d[1]) + (d[2] + d[3]));
;         R[row] = rsqrtf(t * (1.0f / DM) + 1e-6f);
;     }
; __global__ void __launch_bounds__(NWAVES * 64, 2) fwd_mega(Params p) {
;     ...
;                 rfactor_phase(SS, RF);
;                 if (Mrows > MLAT) norm_phase(xlat, xctx, XC, (const float*)(ws + WS_P), sub == 2 ? 4 : 11, Hs, RF, p.norm_g + (size_t)(l * 3 + sub) * DM, modl, 3 * sub, MLAT, Mrows);
.LBB0_158:
	s_or_b32 s2, s94, s92
	s_cmp_eq_u32 s2, 0
	s_cselect_b64 s[28:29], -1, 0
	v_readlane_b32 s8, v253, 5
	s_and_b64 vcc, s[28:29], exec
	v_readlane_b32 s9, v253, 6
	s_cselect_b32 s2, s9, s57
	v_writelane_b32 v252, s2, 46
	s_cselect_b32 s2, s8, s56
	s_cmp_eq_u32 s94, 2
	s_cselect_b64 s[96:97], -1, 0
	v_writelane_b32 v252, s2, 47
	s_and_b64 s[2:3], s[96:97], exec
	v_readlane_b32 s2, v252, 25
	v_readlane_b32 s22, v253, 19
	v_readlane_b32 s23, v253, 20
	v_readlane_b32 s3, v252, 26
	s_cselect_b32 s22, s66, s68
	s_cselect_b32 s23, s67, s69
	s_and_b64 s[26:27], s[2:3], s[96:97]
	s_and_b64 s[2:3], s[26:27], exec
	v_readlane_b32 s18, v253, 15
	s_mov_b32 s2, 0x8400
	s_cselect_b32 s2, 0x8000, s2
	s_mov_b32 s18, 0x800000
	v_readlane_b32 s10, v253, 7
	v_readlane_b32 s11, v253, 8
	v_readlane_b32 s12, v253, 9
	v_readlane_b32 s13, v253, 10
	v_readlane_b32 s14, v253, 11
	v_readlane_b32 s15, v253, 12
	v_readlane_b32 s16, v253, 13
	v_readlane_b32 s17, v253, 14
	v_readlane_b32 s19, v253, 16
	v_readlane_b32 s20, v253, 17
	v_readlane_b32 s21, v253, 18
	s_cbranch_vccnz .LBB0_222
	v_mov_b32_e32 v0, v196
	v_readlane_b32 s3, v253, 32
	v_readlane_b32 s100, v253, 0
	s_cmp_lg_u32 s100, 0x100
	s_cbranch_scc1 .Lrf_keep
	s_sub_i32 s3, s3, 0x18000
.Lrf_keep:
	s_nop 1
	v_add_u32_e32 v0, s3, v0
	s_mov_b32 s3, 0x8000
	v_cmp_gt_u32_e32 vcc, s3, v0
	s_and_saveexec_b64 s[30:31], vcc
	s_cbranch_execz .LBB0_162
	s_mov_b64 s[34:35], 0
